# code placement: peeled first-iteration entries also aligned to 64 bytes (on top of aligned K-loop heads)
# speedup vs baseline: 1.0064x; 1.0064x over previous
;     __device__ __forceinline__ const char* tile(const Unit& u, int t) const { return A + (size_t)u.pm * 2 * hstep() + (size_t)t * (BK * 2); }
;     __device__ __forceinline__ const char* tile(const Unit& u, int t) const { return U + (long)(t >> 2) * xoff + (size_t)u.pn * (1024 * 512) + (size_t)u.pm * 2 * hstep() + (size_t)(t & 3) * (BK * 2); }
;     ...
;         const bool has_next = S.next(ui + 1, nxt);
;         const Unit nu = has_next ? nxt : cur;
;         const char* nB = (const char*)g.Bt + (size_t)nu.pn * 2 * hstepB;
; #pragma unroll 1
;         for (int t = 0; t < nt; t += 2) {
;             const bool last = (t == nt - 2);
;             const char* a1 = AS.tile(cur, t + 1);
;             const char* a2 = last ? AS.tile(nu, 0) : AS.tile(cur, t + 2); const char* b2 = last ? nB : cB + (size_t)(t + 2) * kstep;
;             const char* a3 = last ? AS.tile(nu, 1) : AS.tile(cur, t + 3); const char* b3 = b2 + kstep;
.LBB0_379:
	s_and_b64 s[2:3], exec, s[44:45]
	s_cselect_b32 s3, s26, s73
	s_cselect_b32 s2, s0, s74
	s_ashr_i64 s[24:25], s[2:3], 13
	s_and_b32 s24, s24, 0xfff80000
	s_add_u32 s75, s53, s24
	s_addc_u32 s76, s54, s25
	s_ashr_i32 s1, s0, 31
	s_lshl_b64 s[46:47], s[0:1], 19
	s_add_u32 s1, s55, s46
	s_mov_b32 s48, s97
	s_mov_b32 s49, s2
	s_addc_u32 s77, s56, s47
	s_ashr_i64 s[2:3], s[48:49], 13
	s_add_u32 s78, s55, s2
	s_addc_u32 s79, s56, s3
	s_add_u32 s80, s78, 0x80
	s_addc_u32 s81, s79, 0
	s_add_u32 s82, s69, s28
	v_lshl_add_u64 v[128:129], v[154:155], 0, s[46:47]
	v_lshl_add_u64 v[130:131], v[156:157], 0, s[46:47]
	s_addc_u32 s83, s70, s29
	s_mov_b32 s84, -2
	s_mov_b64 s[2:3], 0
	s_mov_b64 s[90:91], 0x80
	.p2alignl 6, 3212836864

;     __device__ __forceinline__ const char* tile(const Unit& u, int t) const { return A + (size_t)u.pm * 2 * hstep() + (size_t)t * (BK * 2); }
;     __device__ __forceinline__ const char* tile(const Unit& u, int t) const { return U + (long)(t >> 2) * xoff + (size_t)u.pn * (1024 * 512) + (size_t)u.pm * 2 * hstep() + (size_t)(t & 3) * (BK * 2); }
;     ...
;         const bool has_next = S.next(ui + 1, nxt);
;         const Unit nu = has_next ? nxt : cur;
;         const char* nB = (const char*)g.Bt + (size_t)nu.pn * 2 * hstepB;
; #pragma unroll 1
;         for (int t = 0; t < nt; t += 2) {
;             const bool last = (t == nt - 2);
;             const char* a1 = AS.tile(cur, t + 1);
;             const char* a2 = last ? AS.tile(nu, 0) : AS.tile(cur, t + 2); const char* b2 = last ? nB : cB + (size_t)(t + 2) * kstep;
;             const char* a3 = last ? AS.tile(nu, 1) : AS.tile(cur, t + 3); const char* b3 = b2 + kstep;
.LBB0_450:
	s_and_b64 s[0:1], s[40:41], exec
	s_cselect_b32 s21, s53, s55
	s_cselect_b32 s20, s54, s2
	s_ashr_i64 s[0:1], s[20:21], 13
	s_and_b32 s0, s0, 0xfff80000
	s_add_u32 s56, s5, s0
	s_addc_u32 s57, s28, s1
	s_ashr_i32 s3, s2, 31
	s_mov_b32 s26, s97
	s_mov_b32 s27, s20
	s_lshl_b64 s[24:25], s[2:3], 19
	s_ashr_i64 s[20:21], s[26:27], 13
	s_add_u32 s3, s29, s20
	s_addc_u32 s58, s30, s21
	s_add_u32 s59, s3, 0x80
	s_addc_u32 s60, s58, 0
	v_readlane_b32 s20, v254, 33
	v_readlane_b32 s21, v254, 34
	s_add_u32 s61, s20, s24
	s_addc_u32 s64, s21, s25
	s_add_u32 s65, s50, s18
	s_mov_b64 s[72:73], 0x80
	v_lshl_add_u64 v[112:113], v[166:167], 0, s[24:25]
	v_lshl_add_u64 v[114:115], v[168:169], 0, s[24:25]
	s_addc_u32 s66, s51, s19
	s_mov_b32 s67, -2
	s_mov_b64 s[18:19], 0
	.p2alignl 6, 3212836864

;     __device__ __forceinline__ const char* tile(const Unit& u, int t) const { return A + (size_t)u.pm * 2 * hstep() + (size_t)t * (BK * 2); }
;     __device__ __forceinline__ const char* tile(const Unit& u, int t) const { return U + (long)(t >> 2) * xoff + (size_t)u.pn * (1024 * 512) + (size_t)u.pm * 2 * hstep() + (size_t)(t & 3) * (BK * 2); }
;     ...
;         const bool has_next = S.next(ui + 1, nxt);
;         const Unit nu = has_next ? nxt : cur;
;         const char* nB = (const char*)g.Bt + (size_t)nu.pn * 2 * hstepB;
; #pragma unroll 1
;         for (int t = 0; t < nt; t += 2) {
;             const bool last = (t == nt - 2);
;             const char* a1 = AS.tile(cur, t + 1);
;             const char* a2 = last ? AS.tile(nu, 0) : AS.tile(cur, t + 2); const char* b2 = last ? nB : cB + (size_t)(t + 2) * kstep;
;             const char* a3 = last ? AS.tile(nu, 1) : AS.tile(cur, t + 3); const char* b3 = b2 + kstep;
.LBB0_503:
	s_and_b64 s[8:9], s[38:39], exec
	s_cselect_b32 s15, s44, s46
	s_cselect_b32 s14, s45, s10
	s_ashr_i64 s[8:9], s[14:15], 13
	s_and_b32 s8, s8, 0xfff80000
	s_add_u32 s47, s5, s8
	s_addc_u32 s48, s20, s9
	s_ashr_i32 s11, s10, 31
	s_mov_b32 s18, s97
	s_mov_b32 s19, s14
	s_lshl_b64 s[16:17], s[10:11], 19
	s_ashr_i64 s[14:15], s[18:19], 13
	s_add_u32 s11, s21, s14
	s_addc_u32 s49, s24, s15
	s_add_u32 s50, s11, 0x80
	s_addc_u32 s51, s49, 0
	v_readlane_b32 s14, v254, 33
	v_readlane_b32 s15, v254, 34
	s_add_u32 s52, s14, s16
	s_addc_u32 s53, s15, s17
	s_add_u32 s54, s35, s12
	v_lshl_add_u64 v[142:143], v[138:139], 0, s[16:17]
	v_lshl_add_u64 v[144:145], v[140:141], 0, s[16:17]
	s_addc_u32 s55, s42, s13
	s_mov_b32 s56, -2
	s_mov_b64 s[12:13], 0
	s_mov_b64 s[64:65], 0x80
	.p2alignl 6, 3212836864

;     __device__ __forceinline__ const char* tile(const Unit& u, int t) const { return A + (size_t)u.pm * 2 * hstep() + (size_t)t * (BK * 2); }
;     __device__ __forceinline__ const char* tile(const Unit& u, int t) const { return U + (long)(t >> 2) * xoff + (size_t)u.pn * (1024 * 512) + (size_t)u.pm * 2 * hstep() + (size_t)(t & 3) * (BK * 2); }
;     ...
;         const bool has_next = S.next(ui + 1, nxt);
;         const Unit nu = has_next ? nxt : cur;
;         const char* nB = (const char*)g.Bt + (size_t)nu.pn * 2 * hstepB;
; #pragma unroll 1
;         for (int t = 0; t < nt; t += 2) {
;             const bool last = (t == nt - 2);
;             const char* a1 = AS.tile(cur, t + 1);
;             const char* a2 = last ? AS.tile(nu, 0) : AS.tile(cur, t + 2); const char* b2 = last ? nB : cB + (size_t)(t + 2) * kstep;
;             const char* a3 = last ? AS.tile(nu, 1) : AS.tile(cur, t + 3); const char* b3 = b2 + kstep;
.LBB0_533:
	s_and_b64 s[16:17], s[38:39], exec
	s_cselect_b32 s21, s56, s58
	s_cselect_b32 s20, s57, s0
	s_ashr_i64 s[16:17], s[20:21], 31
	s_and_b32 s16, s16, -2
	s_lshl_b64 s[16:17], s[16:17], s52
	s_add_u32 s40, s26, s16
	s_addc_u32 s41, s27, s17
	s_ashr_i32 s1, s0, 31
	s_bfe_i64 s[20:21], s[20:21], 0x200000
	s_lshl_b64 s[68:69], s[0:1], s31
	s_lshl_b64 s[20:21], s[20:21], s31
	s_add_u32 s1, s29, s20
	s_addc_u32 s59, s30, s21
	s_add_u32 s60, s1, 0x80
	s_addc_u32 s61, s59, 0
	s_add_u32 s64, s28, s68
	s_addc_u32 s65, 0, s69
	s_add_u32 s66, s53, s2
	v_readlane_b32 s82, v254, 33
	s_mov_b32 s80, s74
	s_addc_u32 s67, s54, s3
	v_lshl_add_u64 v[64:65], v[204:205], 0, s[68:69]
	v_lshl_add_u64 v[66:67], v[206:207], 0, s[68:69]
	s_mov_b32 s2, 0
	s_waitcnt lgkmcnt(0)
	s_mov_b64 s[76:77], 0x80
	s_mov_b64 s[78:79], 0x100
	v_readlane_b32 s83, v254, 34
	.p2alignl 6, 3212836864

;     __device__ __forceinline__ const char* tile(const Unit& u, int t) const { return A + (size_t)u.pm * 2 * hstep() + (size_t)t * (BK * 2); }
;     __device__ __forceinline__ const char* tile(const Unit& u, int t) const { return U + (long)(t >> 2) * xoff + (size_t)u.pn * (1024 * 512) + (size_t)u.pm * 2 * hstep() + (size_t)(t & 3) * (BK * 2); }
;     ...
;         const bool has_next = S.next(ui + 1, nxt);
;         const Unit nu = has_next ? nxt : cur;
;         const char* nB = (const char*)g.Bt + (size_t)nu.pn * 2 * hstepB;
; #pragma unroll 1
;         for (int t = 0; t < nt; t += 2) {
;             const bool last = (t == nt - 2);
;             const char* a1 = AS.tile(cur, t + 1);
;             const char* a2 = last ? AS.tile(nu, 0) : AS.tile(cur, t + 2); const char* b2 = last ? nB : cB + (size_t)(t + 2) * kstep;
;             const char* a3 = last ? AS.tile(nu, 1) : AS.tile(cur, t + 3); const char* b3 = b2 + kstep;
.LBB0_701:
	s_and_b64 s[16:17], s[38:39], exec
	s_cselect_b32 s21, s59, s61
	s_cselect_b32 s20, s60, s18
	s_ashr_i64 s[16:17], s[20:21], 13
	s_and_b32 s16, s16, 0xfff80000
	s_add_u32 s1, s44, s16
	s_addc_u32 s28, s45, s17
	s_ashr_i32 s19, s18, 31
	s_mov_b32 s26, s97
	s_mov_b32 s27, s20
	s_lshl_b64 s[24:25], s[18:19], 19
	s_ashr_i64 s[20:21], s[26:27], 13
	s_add_u32 s19, s46, s20
	s_addc_u32 s29, s47, s21
	s_add_u32 s30, s19, 0x80
	s_addc_u32 s31, s29, 0
	v_readlane_b32 s20, v254, 33
	v_readlane_b32 s21, v254, 34
	s_add_u32 s40, s20, s24
	s_addc_u32 s41, s21, s25
	s_add_u32 s42, s35, s2
	v_lshl_add_u64 v[128:129], v[152:153], 0, s[24:25]
	v_lshl_add_u64 v[130:131], v[154:155], 0, s[24:25]
	s_addc_u32 s43, s56, s3
	s_mov_b32 s62, -2
	s_mov_b64 s[2:3], 0
	s_mov_b64 s[68:69], 0x80
	.p2alignl 6, 3212836864

;     __device__ __forceinline__ size_t hstep() const { return (size_t)HALF * K * 2; }
;     __device__ __forceinline__ const char* tile(const Unit& u, int t) const { return A + (size_t)u.pm * 2 * hstep() + (size_t)t * (BK * 2); }
;     __device__ __forceinline__ size_t hstep() const { return (size_t)HALF * 512; }
;     __device__ __forceinline__ const char* tile(const Unit& u, int t) const { return U + (long)(t >> 2) * xoff + (size_t)u.pn * (1024 * 512) + (size_t)u.pm * 2 * hstep() + (size_t)(t & 3) * (BK * 2); }
;     ...
;         const bool has_next = S.next(ui + 1, nxt);
;         const Unit nu = has_next ? nxt : cur;
;         const char* nB = (const char*)g.Bt + (size_t)nu.pn * 2 * hstepB;
; #pragma unroll 1
;         for (int t = 0; t < nt; t += 2) {
;             const bool last = (t == nt - 2);
;             const char* a1 = AS.tile(cur, t + 1);
;             const char* a2 = last ? AS.tile(nu, 0) : AS.tile(cur, t + 2); const char* b2 = last ? nB : cB + (size_t)(t + 2) * kstep;
;             const char* a3 = last ? AS.tile(nu, 1) : AS.tile(cur, t + 3); const char* b3 = b2 + kstep;
.LBB0_784:
	s_and_b64 s[6:7], s[38:39], exec
	s_cselect_b32 s16, s43, s10
	s_cselect_b32 s15, s44, s8
	s_ashr_i32 s17, s16, 31
	s_lshl_b64 s[6:7], s[16:17], 17
	s_add_u32 s45, s28, s6
	s_addc_u32 s46, s29, s7
	s_ashr_i32 s11, s10, 31
	s_lshl_b64 s[10:11], s[10:11], 19
	v_readlane_b32 s21, v254, 37
	s_add_u32 s14, s21, s10
	v_readlane_b32 s22, v254, 38
	s_addc_u32 s20, s22, s11
	s_ashr_i32 s9, s8, 31
	s_lshl_b64 s[18:19], s[8:9], 17
	s_add_u32 s9, s14, s18
	s_addc_u32 s47, s20, s19
	s_lshl_b64 s[16:17], s[16:17], 19
	s_add_u32 s18, s21, s16
	s_mov_b32 s14, 0
	s_addc_u32 s19, s22, s17
	s_ashr_i64 s[16:17], s[14:15], 15
	s_add_u32 s48, s18, s16
	s_addc_u32 s49, s19, s17
	s_add_u32 s50, s48, 0x80
	s_addc_u32 s51, s49, 0
	s_add_u32 s52, s28, s12
	s_addc_u32 s53, s29, s13
	s_mov_b64 s[12:13], -1
	s_mov_b64 s[16:17], 0
	s_mov_b64 s[66:67], 0x80
	.p2alignl 6, 3212836864
